# skinny_dot chains of the meta-row projections (phases 3,4,5,7 prefix): all fragment loads hoisted, counted waits
# speedup vs baseline: 1.0021x; 1.0021x over previous
.LBB0_68:
	v_add_u32_e32 v8, s24, v12
	v_ashrrev_i32_e32 v9, 31, v8
	v_lshlrev_b64 v[8:9], 11, v[8:9]
	v_lshl_add_u64 v[22:23], v[4:5], 0, v[8:9]
	global_load_dwordx4 v[60:63], v[22:23], off
	global_load_dwordx4 v[64:67], v[0:1], off
	global_load_dwordx4 v[68:71], v[22:23], off offset:64
	global_load_dwordx4 v[72:75], v[0:1], off offset:64
	global_load_dwordx4 v[76:79], v[22:23], off offset:128
	global_load_dwordx4 v[80:83], v[0:1], off offset:128
	global_load_dwordx4 v[84:87], v[22:23], off offset:192
	global_load_dwordx4 v[88:91], v[0:1], off offset:192
	s_waitcnt vmcnt(6)
	v_mfma_f32_16x16x32_bf16 v[8:11], v[60:63], v[64:67], 0
	s_waitcnt vmcnt(4)
	v_mfma_f32_16x16x32_bf16 v[8:11], v[68:71], v[72:75], v[8:11]
	s_waitcnt vmcnt(2)
	v_mfma_f32_16x16x32_bf16 v[8:11], v[76:79], v[80:83], v[8:11]
	s_barrier
	s_waitcnt vmcnt(0)
	v_mfma_f32_16x16x32_bf16 v[8:11], v[84:87], v[88:91], v[8:11]
	s_nop 7
	ds_write_b128 v13, v[8:11]
	v_mov_b32_e32 v8, 0
	v_mov_b32_e32 v9, 0
	v_mov_b32_e32 v10, 0
	v_mov_b32_e32 v11, 0
	s_waitcnt lgkmcnt(0)
	s_barrier
	s_and_saveexec_b64 s[38:39], vcc
	s_cbranch_execz .LBB0_70
	ds_read_b128 v[8:11], v13
	s_waitcnt lgkmcnt(0)
	v_pk_add_f32 v[14:15], v[10:11], 0 op_sel_hi:[1,0]
	v_pk_add_f32 v[16:17], v[8:9], 0 op_sel_hi:[1,0]
	ds_read_b128 v[8:11], v13 offset:1024
	s_waitcnt lgkmcnt(0)
	v_pk_add_f32 v[14:15], v[14:15], v[10:11]
	v_pk_add_f32 v[16:17], v[16:17], v[8:9]
	ds_read_b128 v[8:11], v13 offset:2048
	s_waitcnt lgkmcnt(0)
	v_pk_add_f32 v[14:15], v[14:15], v[10:11]
	v_pk_add_f32 v[16:17], v[16:17], v[8:9]
	ds_read_b128 v[8:11], v13 offset:3072
	s_waitcnt lgkmcnt(0)
	v_pk_add_f32 v[14:15], v[14:15], v[10:11]
	v_pk_add_f32 v[16:17], v[16:17], v[8:9]
	ds_read_b128 v[8:11], v13 offset:4096
	s_waitcnt lgkmcnt(0)
	v_pk_add_f32 v[14:15], v[14:15], v[10:11]
	v_pk_add_f32 v[16:17], v[16:17], v[8:9]
	ds_read_b128 v[8:11], v13 offset:5120
	s_waitcnt lgkmcnt(0)
	v_pk_add_f32 v[14:15], v[14:15], v[10:11]
	v_pk_add_f32 v[16:17], v[16:17], v[8:9]
	ds_read_b128 v[8:11], v13 offset:6144
	s_waitcnt lgkmcnt(0)
	v_pk_add_f32 v[14:15], v[14:15], v[10:11]
	v_pk_add_f32 v[16:17], v[16:17], v[8:9]
	ds_read_b128 v[8:11], v13 offset:7168
	s_waitcnt lgkmcnt(0)
	v_pk_add_f32 v[10:11], v[14:15], v[10:11]
	v_pk_add_f32 v[8:9], v[16:17], v[8:9]

.LBB0_117:
	v_add_u32_e32 v8, s38, v12
	v_ashrrev_i32_e32 v9, 31, v8
	v_lshlrev_b64 v[8:9], 11, v[8:9]
	v_lshl_add_u64 v[22:23], v[4:5], 0, v[8:9]
	global_load_dwordx4 v[60:63], v[22:23], off
	global_load_dwordx4 v[64:67], v[0:1], off
	global_load_dwordx4 v[68:71], v[22:23], off offset:64
	global_load_dwordx4 v[72:75], v[0:1], off offset:64
	global_load_dwordx4 v[76:79], v[22:23], off offset:128
	global_load_dwordx4 v[80:83], v[0:1], off offset:128
	global_load_dwordx4 v[84:87], v[22:23], off offset:192
	global_load_dwordx4 v[88:91], v[0:1], off offset:192
	s_waitcnt vmcnt(6)
	v_mfma_f32_16x16x32_bf16 v[8:11], v[60:63], v[64:67], 0
	s_waitcnt vmcnt(4)
	v_mfma_f32_16x16x32_bf16 v[8:11], v[68:71], v[72:75], v[8:11]
	s_waitcnt vmcnt(2)
	v_mfma_f32_16x16x32_bf16 v[8:11], v[76:79], v[80:83], v[8:11]
	s_barrier
	s_waitcnt vmcnt(0)
	v_mfma_f32_16x16x32_bf16 v[8:11], v[84:87], v[88:91], v[8:11]
	s_nop 7
	ds_write_b128 v2, v[8:11]
	v_mov_b32_e32 v8, 0
	v_mov_b32_e32 v9, 0
	v_mov_b32_e32 v10, 0
	v_mov_b32_e32 v11, 0
	s_waitcnt lgkmcnt(0)
	s_barrier
	s_and_saveexec_b64 s[40:41], vcc
	s_cbranch_execz .LBB0_119
	ds_read_b128 v[8:11], v2
	s_waitcnt lgkmcnt(0)
	v_pk_add_f32 v[14:15], v[10:11], 0 op_sel_hi:[1,0]
	v_pk_add_f32 v[16:17], v[8:9], 0 op_sel_hi:[1,0]
	ds_read_b128 v[8:11], v2 offset:1024
	s_waitcnt lgkmcnt(0)
	v_pk_add_f32 v[14:15], v[14:15], v[10:11]
	v_pk_add_f32 v[16:17], v[16:17], v[8:9]
	ds_read_b128 v[8:11], v2 offset:2048
	s_waitcnt lgkmcnt(0)
	v_pk_add_f32 v[14:15], v[14:15], v[10:11]
	v_pk_add_f32 v[16:17], v[16:17], v[8:9]
	ds_read_b128 v[8:11], v2 offset:3072
	s_waitcnt lgkmcnt(0)
	v_pk_add_f32 v[14:15], v[14:15], v[10:11]
	v_pk_add_f32 v[16:17], v[16:17], v[8:9]
	ds_read_b128 v[8:11], v2 offset:4096
	s_waitcnt lgkmcnt(0)
	v_pk_add_f32 v[14:15], v[14:15], v[10:11]
	v_pk_add_f32 v[16:17], v[16:17], v[8:9]
	ds_read_b128 v[8:11], v2 offset:5120
	s_waitcnt lgkmcnt(0)
	v_pk_add_f32 v[14:15], v[14:15], v[10:11]
	v_pk_add_f32 v[16:17], v[16:17], v[8:9]
	ds_read_b128 v[8:11], v2 offset:6144
	s_waitcnt lgkmcnt(0)
	v_pk_add_f32 v[14:15], v[14:15], v[10:11]
	v_pk_add_f32 v[16:17], v[16:17], v[8:9]
	ds_read_b128 v[8:11], v2 offset:7168
	s_waitcnt lgkmcnt(0)
	v_pk_add_f32 v[10:11], v[14:15], v[10:11]
	v_pk_add_f32 v[8:9], v[16:17], v[8:9]

.LBB0_149:
	v_add_u32_e32 v2, s40, v24
	s_movk_i32 s0, 0xc00
	v_mad_i64_i32 v[22:23], s[0:1], v2, s0, 0
	v_lshl_add_u64 v[20:21], v[22:23], 1, v[4:5]
	global_load_dwordx4 v[60:63], v[20:21], off
	global_load_dwordx4 v[64:67], v[0:1], off
	global_load_dwordx4 v[68:71], v[20:21], off offset:64
	global_load_dwordx4 v[72:75], v[0:1], off offset:64
	global_load_dwordx4 v[76:79], v[20:21], off offset:128
	global_load_dwordx4 v[80:83], v[0:1], off offset:128
	global_load_dwordx4 v[84:87], v[20:21], off offset:192
	global_load_dwordx4 v[88:91], v[0:1], off offset:192
	global_load_dwordx4 v[92:95], v[20:21], off offset:256
	global_load_dwordx4 v[96:99], v[0:1], off offset:256
	global_load_dwordx4 v[100:103], v[20:21], off offset:320
	global_load_dwordx4 v[104:107], v[0:1], off offset:320
	global_load_dwordx4 v[108:111], v[20:21], off offset:384
	global_load_dwordx4 v[112:115], v[0:1], off offset:384
	global_load_dwordx4 v[116:119], v[20:21], off offset:448
	global_load_dwordx4 v[120:123], v[0:1], off offset:448
	s_waitcnt vmcnt(14)
	v_mfma_f32_16x16x32_bf16 v[16:19], v[60:63], v[64:67], 0
	s_waitcnt vmcnt(12)
	v_mfma_f32_16x16x32_bf16 v[16:19], v[68:71], v[72:75], v[16:19]
	s_waitcnt vmcnt(10)
	v_mfma_f32_16x16x32_bf16 v[16:19], v[76:79], v[80:83], v[16:19]
	s_waitcnt vmcnt(8)
	v_mfma_f32_16x16x32_bf16 v[16:19], v[84:87], v[88:91], v[16:19]
	s_waitcnt vmcnt(6)
	v_mfma_f32_16x16x32_bf16 v[16:19], v[92:95], v[96:99], v[16:19]
	s_waitcnt vmcnt(4)
	v_mfma_f32_16x16x32_bf16 v[16:19], v[100:103], v[104:107], v[16:19]
	s_waitcnt vmcnt(2)
	v_mfma_f32_16x16x32_bf16 v[16:19], v[108:111], v[112:115], v[16:19]
	s_barrier
	v_mov_b32_e32 v20, 0
	v_mov_b32_e32 v21, 0
	s_waitcnt vmcnt(0)
	v_mfma_f32_16x16x32_bf16 v[16:19], v[116:119], v[120:123], v[16:19]
	s_nop 7
	ds_write_b128 v25, v[16:19]
	v_mov_b32_e32 v18, 0
	v_mov_b32_e32 v16, 0
	v_mov_b32_e32 v17, 0
	s_waitcnt lgkmcnt(0)
	s_barrier
	s_and_saveexec_b64 s[0:1], vcc
	s_cbranch_execz .LBB0_151
	ds_read_b128 v[26:29], v25
	s_waitcnt lgkmcnt(0)
	v_pk_add_f32 v[16:17], v[28:29], 0 op_sel_hi:[1,0]
	v_pk_add_f32 v[20:21], v[26:27], 0 op_sel_hi:[1,0]
	ds_read_b128 v[26:29], v25 offset:1024
	s_waitcnt lgkmcnt(0)
	v_pk_add_f32 v[16:17], v[16:17], v[28:29]
	v_pk_add_f32 v[20:21], v[20:21], v[26:27]
	ds_read_b128 v[26:29], v25 offset:2048
	s_waitcnt lgkmcnt(0)
	v_pk_add_f32 v[16:17], v[16:17], v[28:29]
	v_pk_add_f32 v[20:21], v[20:21], v[26:27]
	ds_read_b128 v[26:29], v25 offset:3072
	s_waitcnt lgkmcnt(0)
	v_pk_add_f32 v[16:17], v[16:17], v[28:29]
	v_pk_add_f32 v[20:21], v[20:21], v[26:27]
	ds_read_b128 v[26:29], v25 offset:4096
	s_waitcnt lgkmcnt(0)
	v_pk_add_f32 v[16:17], v[16:17], v[28:29]
	v_pk_add_f32 v[20:21], v[20:21], v[26:27]
	ds_read_b128 v[26:29], v25 offset:5120
	s_waitcnt lgkmcnt(0)
	v_pk_add_f32 v[16:17], v[16:17], v[28:29]
	v_pk_add_f32 v[20:21], v[20:21], v[26:27]
	ds_read_b128 v[26:29], v25 offset:6144
	s_waitcnt lgkmcnt(0)
	v_pk_add_f32 v[16:17], v[16:17], v[28:29]
	v_pk_add_f32 v[20:21], v[20:21], v[26:27]
	ds_read_b128 v[26:29], v25 offset:7168
	s_waitcnt lgkmcnt(0)
	v_pk_add_f32 v[16:17], v[16:17], v[28:29]
	v_pk_add_f32 v[20:21], v[20:21], v[26:27]
.LBB0_151:
	s_or_b64 exec, exec, s[0:1]
	v_lshl_add_u64 v[22:23], v[22:23], 1, v[8:9]
	global_load_dwordx4 v[60:63], v[22:23], off
	global_load_dwordx4 v[64:67], v[6:7], off
	global_load_dwordx4 v[68:71], v[22:23], off offset:64
	global_load_dwordx4 v[72:75], v[6:7], off offset:64
	global_load_dwordx4 v[76:79], v[22:23], off offset:128
	global_load_dwordx4 v[80:83], v[6:7], off offset:128
	global_load_dwordx4 v[84:87], v[22:23], off offset:192
	global_load_dwordx4 v[88:91], v[6:7], off offset:192
	v_mov_b32_e32 v19, 0
	s_waitcnt vmcnt(6)
	v_mfma_f32_16x16x32_bf16 v[26:29], v[60:63], v[64:67], 0
	s_waitcnt vmcnt(4)
	v_mfma_f32_16x16x32_bf16 v[26:29], v[68:71], v[72:75], v[26:29]
	s_waitcnt vmcnt(2)
	v_mfma_f32_16x16x32_bf16 v[26:29], v[76:79], v[80:83], v[26:29]
	v_mov_b32_e32 v22, 0
	v_mov_b32_e32 v23, 0
	s_barrier
	s_waitcnt vmcnt(0)
	v_mfma_f32_16x16x32_bf16 v[26:29], v[84:87], v[88:91], v[26:29]
	s_nop 7
	ds_write_b128 v25, v[26:29]
	s_waitcnt lgkmcnt(0)
	s_barrier
	s_and_saveexec_b64 s[0:1], vcc
	s_cbranch_execz .LBB0_153
	ds_read_b128 v[26:29], v25
	s_waitcnt lgkmcnt(0)
	v_pk_add_f32 v[18:19], v[28:29], 0 op_sel_hi:[1,0]
	v_pk_add_f32 v[22:23], v[26:27], 0 op_sel_hi:[1,0]
	ds_read_b128 v[26:29], v25 offset:1024
	s_waitcnt lgkmcnt(0)
	v_pk_add_f32 v[18:19], v[18:19], v[28:29]
	v_pk_add_f32 v[22:23], v[22:23], v[26:27]
	ds_read_b128 v[26:29], v25 offset:2048
	s_waitcnt lgkmcnt(0)
	v_pk_add_f32 v[18:19], v[18:19], v[28:29]
	v_pk_add_f32 v[22:23], v[22:23], v[26:27]
	ds_read_b128 v[26:29], v25 offset:3072
	s_waitcnt lgkmcnt(0)
	v_pk_add_f32 v[18:19], v[18:19], v[28:29]
	v_pk_add_f32 v[22:23], v[22:23], v[26:27]
	ds_read_b128 v[26:29], v25 offset:4096
	s_waitcnt lgkmcnt(0)
	v_pk_add_f32 v[18:19], v[18:19], v[28:29]
	v_pk_add_f32 v[22:23], v[22:23], v[26:27]
	ds_read_b128 v[26:29], v25 offset:5120
	s_waitcnt lgkmcnt(0)
	v_pk_add_f32 v[18:19], v[18:19], v[28:29]
	v_pk_add_f32 v[22:23], v[22:23], v[26:27]
	ds_read_b128 v[26:29], v25 offset:6144
	s_waitcnt lgkmcnt(0)
	v_pk_add_f32 v[18:19], v[18:19], v[28:29]
	v_pk_add_f32 v[30:31], v[22:23], v[26:27]
	ds_read_b128 v[26:29], v25 offset:7168
	s_waitcnt lgkmcnt(0)
	v_pk_add_f32 v[22:23], v[18:19], v[28:29]
	v_pk_add_f32 v[18:19], v[30:31], v[26:27]
